# hyena z-row loads issued together during filter expansion; RG-LRU backward pass rewritten by hand: 32 loads per 8 tokens issued first, same arithmetic
# speedup vs baseline: 1.0448x; 1.0112x over previous
; __device__ __forceinline__ unsigned cvt_pk_bf16(float lo, float hi) { const f32x2_t v = {lo, hi}; const bf16x2_t b = __builtin_convertvector(v, bf16x2_t); return __builtin_bit_cast(unsigned, b); }
; __device__ __forceinline__ float lo_bf(unsigned w) { return __uint_as_float(w << 16); }
; __device__ __forceinline__ float hi_bf(unsigned w) { return __uint_as_float(w & 0xffff0000u); }
; __device__ __forceinline__ float gelu_tanh_(float gx) { const float inner = 0.7978845608028654f * (gx + 0.044715f * gx * gx * gx); const float th = 1.0f - 2.0f * __builtin_amdgcn_rcpf(1.0f + __expf(2.0f * inner)); return 0.5f * gx * (1.0f + th); }
; __device__ void rg_scan_phase(unsigned char* smem, const Params& p) {
;     ...
; #pragma unroll 8
;         for (int i = 0; i < 128; ++i) { const int tt = 127 - i; const unsigned l1 = *(const unsigned*)(la1 + (size_t)tt * 512), v1 = *(const unsigned*)(u1 + (size_t)tt * 512);
;             hbx = __expf(lo_bf(l1)) * hbx + lo_bf(v1); hby = __expf(hi_bf(l1)) * hby + hi_bf(v1);
;             const unsigned gw = *(const unsigned*)(gp + (size_t)tt * 1024), hw = *(const unsigned*)(hfp + (size_t)tt * 512);
;             *(unsigned*)(yo + (size_t)tt * 1536) = cvt_pk_bf16((lo_bf(hw) + hbx) * gelu_tanh_(lo_bf(gw)), (hi_bf(hw) + hby) * gelu_tanh_(hi_bf(gw))); }
.LBB0_181:
	v_lshl_add_u64 v[16:17], s[6:7], 0, v[14:15]
	s_mov_b32 s0, 0x14c1fc00
	s_mov_b32 s1, 0
	v_lshl_add_u64 v[38:39], v[16:17], 0, s[0:1]
	s_mov_b32 s0, 0x18c1fc00
	v_lshl_add_u64 v[56:57], v[16:17], 0, s[0:1]
	s_mov_b32 s0, 0x1ac1fc00
	v_lshl_add_u64 v[58:59], v[16:17], 0, s[0:1]
	v_lshl_add_u64 v[60:61], s[6:7], 0, v[4:5]
	s_mov_b32 s0, 0xdc3fc00
	v_lshl_add_u64 v[60:61], v[60:61], 0, s[0:1]
	v_lshl_add_u64 v[6:7], s[6:7], 0, v[2:3]
	s_mov_b32 s0, 0x1cc5fc00
	v_lshl_add_u64 v[6:7], v[6:7], 0, s[0:1]
	s_mov_b32 s14, 0xfffff000
	s_mov_b32 s15, -1
	s_mov_b32 s16, 0xfffff400
	s_mov_b32 s17, -1
	global_load_dword v16, v[38:39], off
	global_load_dword v17, v[56:57], off
	global_load_dword v18, v[60:61], off
	global_load_dword v19, v[58:59], off
	global_load_dword v20, v[38:39], off offset:-1024
	global_load_dword v21, v[56:57], off offset:-1024
	global_load_dword v22, v[60:61], off offset:-2048
	global_load_dword v23, v[58:59], off offset:-1024
	v_lshl_add_u64 v[60:61], v[60:61], 0, s[14:15]
	global_load_dword v24, v[38:39], off offset:-2048
	global_load_dword v25, v[56:57], off offset:-2048
	global_load_dword v26, v[60:61], off
	global_load_dword v27, v[58:59], off offset:-2048
	global_load_dword v28, v[38:39], off offset:-3072
	global_load_dword v29, v[56:57], off offset:-3072
	global_load_dword v30, v[60:61], off offset:-2048
	global_load_dword v31, v[58:59], off offset:-3072
	v_lshl_add_u64 v[38:39], v[38:39], 0, s[14:15]
	v_lshl_add_u64 v[56:57], v[56:57], 0, s[14:15]
	v_lshl_add_u64 v[58:59], v[58:59], 0, s[14:15]
	v_lshl_add_u64 v[60:61], v[60:61], 0, s[14:15]
	global_load_dword v40, v[38:39], off
	global_load_dword v41, v[56:57], off
	global_load_dword v42, v[60:61], off
	global_load_dword v43, v[58:59], off
	global_load_dword v44, v[38:39], off offset:-1024
	global_load_dword v45, v[56:57], off offset:-1024
	global_load_dword v46, v[60:61], off offset:-2048
	global_load_dword v47, v[58:59], off offset:-1024
	v_lshl_add_u64 v[60:61], v[60:61], 0, s[14:15]
	global_load_dword v48, v[38:39], off offset:-2048
	global_load_dword v49, v[56:57], off offset:-2048
	global_load_dword v50, v[60:61], off
	global_load_dword v51, v[58:59], off offset:-2048
	global_load_dword v52, v[38:39], off offset:-3072
	global_load_dword v53, v[56:57], off offset:-3072
	global_load_dword v54, v[60:61], off offset:-2048
	global_load_dword v55, v[58:59], off offset:-3072
	s_waitcnt vmcnt(28)
	v_and_b32_e32 v56, 0xffff0000, v16
	v_lshlrev_b32_e32 v57, 16, v16
	v_mul_f32_e32 v56, 0x3fb8aa3b, v56
	v_mul_f32_e32 v57, 0x3fb8aa3b, v57
	v_exp_f32_e32 v56, v56
	v_exp_f32_e32 v57, v57
	v_and_b32_e32 v58, 0xffff0000, v17
	v_lshlrev_b32_e32 v59, 16, v17
	v_lshlrev_b32_e32 v60, 16, v18
	v_and_b32_e32 v61, 0xffff0000, v18
	v_pk_fma_f32 v[0:1], v[0:1], v[56:57], v[58:59]
	v_mul_f32_e32 v62, 0x3d372713, v60
	v_mul_f32_e32 v63, 0x3d372713, v61
	v_pk_mul_f32 v[38:39], v[60:61], 0.5 op_sel_hi:[1,0]
	v_mul_f32_e32 v62, v62, v60
	v_mul_f32_e32 v63, v63, v61
	v_fma_f32 v62, v62, v60, v60
	v_fma_f32 v63, v63, v61, v61
	v_mul_f32_e32 v62, 0x3f4c422a, v62
	v_mul_f32_e32 v63, 0x3f4c422a, v63
	v_add_f32_e32 v62, v62, v62
	v_add_f32_e32 v63, v63, v63
	v_mul_f32_e32 v62, 0x3fb8aa3b, v62
	v_mul_f32_e32 v63, 0x3fb8aa3b, v63
	v_exp_f32_e32 v62, v62
	v_exp_f32_e32 v63, v63
	v_lshlrev_b32_e32 v60, 16, v19
	v_and_b32_e32 v61, 0xffff0000, v19
	v_add_f32_e32 v62, 1.0, v62
	v_add_f32_e32 v63, 1.0, v63
	v_rcp_f32_e32 v62, v62
	v_rcp_f32_e32 v63, v63
	v_pk_add_f32 v[60:61], v[0:1], v[60:61] op_sel:[1,0] op_sel_hi:[0,1]
	v_pk_fma_f32 v[62:63], v[62:63], 2.0, 1.0 op_sel_hi:[1,0,0] neg_lo:[1,0,0] neg_hi:[1,0,0]
	s_nop 0
	v_pk_add_f32 v[62:63], v[62:63], 1.0 op_sel_hi:[1,0]
	s_nop 0
	v_pk_mul_f32 v[62:63], v[38:39], v[62:63]
	s_nop 0
	v_pk_mul_f32 v[60:61], v[60:61], v[62:63]
	s_nop 0
	v_cvt_pk_bf16_f32 v60, v60, v61
	global_store_dword v[6:7], v60, off
	v_lshl_add_u64 v[6:7], v[6:7], 0, s[16:17]
	s_waitcnt vmcnt(25)
	v_and_b32_e32 v56, 0xffff0000, v20
	v_lshlrev_b32_e32 v57, 16, v20
	v_mul_f32_e32 v56, 0x3fb8aa3b, v56
	v_mul_f32_e32 v57, 0x3fb8aa3b, v57
	v_exp_f32_e32 v56, v56
	v_exp_f32_e32 v57, v57
	v_and_b32_e32 v58, 0xffff0000, v21
	v_lshlrev_b32_e32 v59, 16, v21
	v_lshlrev_b32_e32 v60, 16, v22
	v_and_b32_e32 v61, 0xffff0000, v22
	v_pk_fma_f32 v[0:1], v[0:1], v[56:57], v[58:59]
	v_mul_f32_e32 v62, 0x3d372713, v60
	v_mul_f32_e32 v63, 0x3d372713, v61
	v_pk_mul_f32 v[38:39], v[60:61], 0.5 op_sel_hi:[1,0]
	v_mul_f32_e32 v62, v62, v60
	v_mul_f32_e32 v63, v63, v61
	v_fma_f32 v62, v62, v60, v60
	v_fma_f32 v63, v63, v61, v61
	v_mul_f32_e32 v62, 0x3f4c422a, v62
	v_mul_f32_e32 v63, 0x3f4c422a, v63
	v_add_f32_e32 v62, v62, v62
	v_add_f32_e32 v63, v63, v63
	v_mul_f32_e32 v62, 0x3fb8aa3b, v62
	v_mul_f32_e32 v63, 0x3fb8aa3b, v63
	v_exp_f32_e32 v62, v62
	v_exp_f32_e32 v63, v63
	v_lshlrev_b32_e32 v60, 16, v23
	v_and_b32_e32 v61, 0xffff0000, v23
	v_add_f32_e32 v62, 1.0, v62
	v_add_f32_e32 v63, 1.0, v63
	v_rcp_f32_e32 v62, v62
	v_rcp_f32_e32 v63, v63
	v_pk_add_f32 v[60:61], v[0:1], v[60:61] op_sel:[1,0] op_sel_hi:[0,1]
	v_pk_fma_f32 v[62:63], v[62:63], 2.0, 1.0 op_sel_hi:[1,0,0] neg_lo:[1,0,0] neg_hi:[1,0,0]
	s_nop 0
	v_pk_add_f32 v[62:63], v[62:63], 1.0 op_sel_hi:[1,0]
	s_nop 0
	v_pk_mul_f32 v[62:63], v[38:39], v[62:63]
	s_nop 0
	v_pk_mul_f32 v[60:61], v[60:61], v[62:63]
	s_nop 0
	v_cvt_pk_bf16_f32 v60, v60, v61
	global_store_dword v[6:7], v60, off
	v_lshl_add_u64 v[6:7], v[6:7], 0, s[16:17]
	s_waitcnt vmcnt(22)
; __device__ __forceinline__ unsigned cvt_pk_bf16(float lo, float hi) { const f32x2_t v = {lo, hi}; const bf16x2_t b = __builtin_convertvector(v, bf16x2_t); return __builtin_bit_cast(unsigned, b); }
; __device__ __forceinline__ float lo_bf(unsigned w) { return __uint_as_float(w << 16); }
; __device__ __forceinline__ float hi_bf(unsigned w) { return __uint_as_float(w & 0xffff0000u); }
; __device__ __forceinline__ float gelu_tanh_(float gx) { const float inner = 0.7978845608028654f * (gx + 0.044715f * gx * gx * gx); const float th = 1.0f - 2.0f * __builtin_amdgcn_rcpf(1.0f + __expf(2.0f * inner)); return 0.5f * gx * (1.0f + th); }
; __device__ void rg_scan_phase(unsigned char* smem, const Params& p) {
;     ...
; #pragma unroll 8
;         for (int i = 0; i < 128; ++i) { const int tt = 127 - i; const unsigned l1 = *(const unsigned*)(la1 + (size_t)tt * 512), v1 = *(const unsigned*)(u1 + (size_t)tt * 512);
;             hbx = __expf(lo_bf(l1)) * hbx + lo_bf(v1); hby = __expf(hi_bf(l1)) * hby + hi_bf(v1);
;             const unsigned gw = *(const unsigned*)(gp + (size_t)tt * 1024), hw = *(const unsigned*)(hfp + (size_t)tt * 512);
;             *(unsigned*)(yo + (size_t)tt * 1536) = cvt_pk_bf16((lo_bf(hw) + hbx) * gelu_tanh_(lo_bf(gw)), (hi_bf(hw) + hby) * gelu_tanh_(hi_bf(gw))); }
	v_and_b32_e32 v56, 0xffff0000, v24
	v_lshlrev_b32_e32 v57, 16, v24
	v_mul_f32_e32 v56, 0x3fb8aa3b, v56
	v_mul_f32_e32 v57, 0x3fb8aa3b, v57
	v_exp_f32_e32 v56, v56
	v_exp_f32_e32 v57, v57
	v_and_b32_e32 v58, 0xffff0000, v25
	v_lshlrev_b32_e32 v59, 16, v25
	v_lshlrev_b32_e32 v60, 16, v26
	v_and_b32_e32 v61, 0xffff0000, v26
	v_pk_fma_f32 v[0:1], v[0:1], v[56:57], v[58:59]
	v_mul_f32_e32 v62, 0x3d372713, v60
	v_mul_f32_e32 v63, 0x3d372713, v61
	v_pk_mul_f32 v[38:39], v[60:61], 0.5 op_sel_hi:[1,0]
	v_mul_f32_e32 v62, v62, v60
	v_mul_f32_e32 v63, v63, v61
	v_fma_f32 v62, v62, v60, v60
	v_fma_f32 v63, v63, v61, v61
	v_mul_f32_e32 v62, 0x3f4c422a, v62
	v_mul_f32_e32 v63, 0x3f4c422a, v63
	v_add_f32_e32 v62, v62, v62
	v_add_f32_e32 v63, v63, v63
	v_mul_f32_e32 v62, 0x3fb8aa3b, v62
	v_mul_f32_e32 v63, 0x3fb8aa3b, v63
	v_exp_f32_e32 v62, v62
	v_exp_f32_e32 v63, v63
	v_lshlrev_b32_e32 v60, 16, v27
	v_and_b32_e32 v61, 0xffff0000, v27
	v_add_f32_e32 v62, 1.0, v62
	v_add_f32_e32 v63, 1.0, v63
	v_rcp_f32_e32 v62, v62
	v_rcp_f32_e32 v63, v63
	v_pk_add_f32 v[60:61], v[0:1], v[60:61] op_sel:[1,0] op_sel_hi:[0,1]
	v_pk_fma_f32 v[62:63], v[62:63], 2.0, 1.0 op_sel_hi:[1,0,0] neg_lo:[1,0,0] neg_hi:[1,0,0]
	s_nop 0
	v_pk_add_f32 v[62:63], v[62:63], 1.0 op_sel_hi:[1,0]
	s_nop 0
	v_pk_mul_f32 v[62:63], v[38:39], v[62:63]
	s_nop 0
	v_pk_mul_f32 v[60:61], v[60:61], v[62:63]
	s_nop 0
	v_cvt_pk_bf16_f32 v60, v60, v61
	global_store_dword v[6:7], v60, off
	v_lshl_add_u64 v[6:7], v[6:7], 0, s[16:17]
	s_waitcnt vmcnt(19)
	v_and_b32_e32 v56, 0xffff0000, v28
	v_lshlrev_b32_e32 v57, 16, v28
	v_mul_f32_e32 v56, 0x3fb8aa3b, v56
	v_mul_f32_e32 v57, 0x3fb8aa3b, v57
	v_exp_f32_e32 v56, v56
	v_exp_f32_e32 v57, v57
	v_and_b32_e32 v58, 0xffff0000, v29
	v_lshlrev_b32_e32 v59, 16, v29
	v_lshlrev_b32_e32 v60, 16, v30
	v_and_b32_e32 v61, 0xffff0000, v30
	v_pk_fma_f32 v[0:1], v[0:1], v[56:57], v[58:59]
	v_mul_f32_e32 v62, 0x3d372713, v60
	v_mul_f32_e32 v63, 0x3d372713, v61
	v_pk_mul_f32 v[38:39], v[60:61], 0.5 op_sel_hi:[1,0]
	v_mul_f32_e32 v62, v62, v60
	v_mul_f32_e32 v63, v63, v61
	v_fma_f32 v62, v62, v60, v60
	v_fma_f32 v63, v63, v61, v61
	v_mul_f32_e32 v62, 0x3f4c422a, v62
	v_mul_f32_e32 v63, 0x3f4c422a, v63
	v_add_f32_e32 v62, v62, v62
	v_add_f32_e32 v63, v63, v63
	v_mul_f32_e32 v62, 0x3fb8aa3b, v62
	v_mul_f32_e32 v63, 0x3fb8aa3b, v63
	v_exp_f32_e32 v62, v62
	v_exp_f32_e32 v63, v63
	v_lshlrev_b32_e32 v60, 16, v31
	v_and_b32_e32 v61, 0xffff0000, v31
	v_add_f32_e32 v62, 1.0, v62
	v_add_f32_e32 v63, 1.0, v63
	v_rcp_f32_e32 v62, v62
	v_rcp_f32_e32 v63, v63
	v_pk_add_f32 v[60:61], v[0:1], v[60:61] op_sel:[1,0] op_sel_hi:[0,1]
	v_pk_fma_f32 v[62:63], v[62:63], 2.0, 1.0 op_sel_hi:[1,0,0] neg_lo:[1,0,0] neg_hi:[1,0,0]
	s_nop 0
	v_pk_add_f32 v[62:63], v[62:63], 1.0 op_sel_hi:[1,0]
	s_nop 0
	v_pk_mul_f32 v[62:63], v[38:39], v[62:63]
	s_nop 0
	v_pk_mul_f32 v[60:61], v[60:61], v[62:63]
	s_nop 0
	v_cvt_pk_bf16_f32 v60, v60, v61
	global_store_dword v[6:7], v60, off
	v_lshl_add_u64 v[6:7], v[6:7], 0, s[16:17]
	s_waitcnt vmcnt(16)
	v_and_b32_e32 v56, 0xffff0000, v40
	v_lshlrev_b32_e32 v57, 16, v40
	v_mul_f32_e32 v56, 0x3fb8aa3b, v56
	v_mul_f32_e32 v57, 0x3fb8aa3b, v57
	v_exp_f32_e32 v56, v56
	v_exp_f32_e32 v57, v57
	v_and_b32_e32 v58, 0xffff0000, v41
	v_lshlrev_b32_e32 v59, 16, v41
	v_lshlrev_b32_e32 v60, 16, v42
	v_and_b32_e32 v61, 0xffff0000, v42
	v_pk_fma_f32 v[0:1], v[0:1], v[56:57], v[58:59]
	v_mul_f32_e32 v62, 0x3d372713, v60
	v_mul_f32_e32 v63, 0x3d372713, v61
	v_pk_mul_f32 v[38:39], v[60:61], 0.5 op_sel_hi:[1,0]
	v_mul_f32_e32 v62, v62, v60
	v_mul_f32_e32 v63, v63, v61
	v_fma_f32 v62, v62, v60, v60
	v_fma_f32 v63, v63, v61, v61
	v_mul_f32_e32 v62, 0x3f4c422a, v62
	v_mul_f32_e32 v63, 0x3f4c422a, v63
	v_add_f32_e32 v62, v62, v62
	v_add_f32_e32 v63, v63, v63
	v_mul_f32_e32 v62, 0x3fb8aa3b, v62
	v_mul_f32_e32 v63, 0x3fb8aa3b, v63
	v_exp_f32_e32 v62, v62
	v_exp_f32_e32 v63, v63
	v_lshlrev_b32_e32 v60, 16, v43
	v_and_b32_e32 v61, 0xffff0000, v43
	v_add_f32_e32 v62, 1.0, v62
	v_add_f32_e32 v63, 1.0, v63
	v_rcp_f32_e32 v62, v62
	v_rcp_f32_e32 v63, v63
	v_pk_add_f32 v[60:61], v[0:1], v[60:61] op_sel:[1,0] op_sel_hi:[0,1]
	v_pk_fma_f32 v[62:63], v[62:63], 2.0, 1.0 op_sel_hi:[1,0,0] neg_lo:[1,0,0] neg_hi:[1,0,0]
	s_nop 0
	v_pk_add_f32 v[62:63], v[62:63], 1.0 op_sel_hi:[1,0]
	s_nop 0
	v_pk_mul_f32 v[62:63], v[38:39], v[62:63]
	s_nop 0
	v_pk_mul_f32 v[60:61], v[60:61], v[62:63]
	s_nop 0
	v_cvt_pk_bf16_f32 v60, v60, v61
	global_store_dword v[6:7], v60, off
	v_lshl_add_u64 v[6:7], v[6:7], 0, s[16:17]
	s_waitcnt vmcnt(13)
; __device__ __forceinline__ unsigned cvt_pk_bf16(float lo, float hi) { const f32x2_t v = {lo, hi}; const bf16x2_t b = __builtin_convertvector(v, bf16x2_t); return __builtin_bit_cast(unsigned, b); }
; __device__ __forceinline__ float lo_bf(unsigned w) { return __uint_as_float(w << 16); }
; __device__ __forceinline__ float hi_bf(unsigned w) { return __uint_as_float(w & 0xffff0000u); }
; __device__ __forceinline__ float gelu_tanh_(float gx) { const float inner = 0.7978845608028654f * (gx + 0.044715f * gx * gx * gx); const float th = 1.0f - 2.0f * __builtin_amdgcn_rcpf(1.0f + __expf(2.0f * inner)); return 0.5f * gx * (1.0f + th); }
; __device__ void rg_scan_phase(unsigned char* smem, const Params& p) {
;     ...
; #pragma unroll 8
;         for (int i = 0; i < 128; ++i) { const int tt = 127 - i; const unsigned l1 = *(const unsigned*)(la1 + (size_t)tt * 512), v1 = *(const unsigned*)(u1 + (size_t)tt * 512);
;             hbx = __expf(lo_bf(l1)) * hbx + lo_bf(v1); hby = __expf(hi_bf(l1)) * hby + hi_bf(v1);
;             const unsigned gw = *(const unsigned*)(gp + (size_t)tt * 1024), hw = *(const unsigned*)(hfp + (size_t)tt * 512);
;             *(unsigned*)(yo + (size_t)tt * 1536) = cvt_pk_bf16((lo_bf(hw) + hbx) * gelu_tanh_(lo_bf(gw)), (hi_bf(hw) + hby) * gelu_tanh_(hi_bf(gw))); }
	v_and_b32_e32 v56, 0xffff0000, v44
	v_lshlrev_b32_e32 v57, 16, v44
	v_mul_f32_e32 v56, 0x3fb8aa3b, v56
	v_mul_f32_e32 v57, 0x3fb8aa3b, v57
	v_exp_f32_e32 v56, v56
	v_exp_f32_e32 v57, v57
	v_and_b32_e32 v58, 0xffff0000, v45
	v_lshlrev_b32_e32 v59, 16, v45
	v_lshlrev_b32_e32 v60, 16, v46
	v_and_b32_e32 v61, 0xffff0000, v46
	v_pk_fma_f32 v[0:1], v[0:1], v[56:57], v[58:59]
	v_mul_f32_e32 v62, 0x3d372713, v60
	v_mul_f32_e32 v63, 0x3d372713, v61
	v_pk_mul_f32 v[38:39], v[60:61], 0.5 op_sel_hi:[1,0]
	v_mul_f32_e32 v62, v62, v60
	v_mul_f32_e32 v63, v63, v61
	v_fma_f32 v62, v62, v60, v60
	v_fma_f32 v63, v63, v61, v61
	v_mul_f32_e32 v62, 0x3f4c422a, v62
	v_mul_f32_e32 v63, 0x3f4c422a, v63
	v_add_f32_e32 v62, v62, v62
	v_add_f32_e32 v63, v63, v63
	v_mul_f32_e32 v62, 0x3fb8aa3b, v62
	v_mul_f32_e32 v63, 0x3fb8aa3b, v63
	v_exp_f32_e32 v62, v62
	v_exp_f32_e32 v63, v63
	v_lshlrev_b32_e32 v60, 16, v47
	v_and_b32_e32 v61, 0xffff0000, v47
	v_add_f32_e32 v62, 1.0, v62
	v_add_f32_e32 v63, 1.0, v63
	v_rcp_f32_e32 v62, v62
	v_rcp_f32_e32 v63, v63
	v_pk_add_f32 v[60:61], v[0:1], v[60:61] op_sel:[1,0] op_sel_hi:[0,1]
	v_pk_fma_f32 v[62:63], v[62:63], 2.0, 1.0 op_sel_hi:[1,0,0] neg_lo:[1,0,0] neg_hi:[1,0,0]
	s_nop 0
	v_pk_add_f32 v[62:63], v[62:63], 1.0 op_sel_hi:[1,0]
	s_nop 0
	v_pk_mul_f32 v[62:63], v[38:39], v[62:63]
	s_nop 0
	v_pk_mul_f32 v[60:61], v[60:61], v[62:63]
	s_nop 0
	v_cvt_pk_bf16_f32 v60, v60, v61
	global_store_dword v[6:7], v60, off
	v_lshl_add_u64 v[6:7], v[6:7], 0, s[16:17]
	s_waitcnt vmcnt(10)
	v_and_b32_e32 v56, 0xffff0000, v48
	v_lshlrev_b32_e32 v57, 16, v48
	v_mul_f32_e32 v56, 0x3fb8aa3b, v56
	v_mul_f32_e32 v57, 0x3fb8aa3b, v57
	v_exp_f32_e32 v56, v56
	v_exp_f32_e32 v57, v57
	v_and_b32_e32 v58, 0xffff0000, v49
	v_lshlrev_b32_e32 v59, 16, v49
	v_lshlrev_b32_e32 v60, 16, v50
	v_and_b32_e32 v61, 0xffff0000, v50
	v_pk_fma_f32 v[0:1], v[0:1], v[56:57], v[58:59]
	v_mul_f32_e32 v62, 0x3d372713, v60
	v_mul_f32_e32 v63, 0x3d372713, v61
	v_pk_mul_f32 v[38:39], v[60:61], 0.5 op_sel_hi:[1,0]
	v_mul_f32_e32 v62, v62, v60
	v_mul_f32_e32 v63, v63, v61
	v_fma_f32 v62, v62, v60, v60
	v_fma_f32 v63, v63, v61, v61
	v_mul_f32_e32 v62, 0x3f4c422a, v62
	v_mul_f32_e32 v63, 0x3f4c422a, v63
	v_add_f32_e32 v62, v62, v62
	v_add_f32_e32 v63, v63, v63
	v_mul_f32_e32 v62, 0x3fb8aa3b, v62
	v_mul_f32_e32 v63, 0x3fb8aa3b, v63
	v_exp_f32_e32 v62, v62
	v_exp_f32_e32 v63, v63
	v_lshlrev_b32_e32 v60, 16, v51
	v_and_b32_e32 v61, 0xffff0000, v51
	v_add_f32_e32 v62, 1.0, v62
	v_add_f32_e32 v63, 1.0, v63
	v_rcp_f32_e32 v62, v62
	v_rcp_f32_e32 v63, v63
	v_pk_add_f32 v[60:61], v[0:1], v[60:61] op_sel:[1,0] op_sel_hi:[0,1]
	v_pk_fma_f32 v[62:63], v[62:63], 2.0, 1.0 op_sel_hi:[1,0,0] neg_lo:[1,0,0] neg_hi:[1,0,0]
	s_nop 0
	v_pk_add_f32 v[62:63], v[62:63], 1.0 op_sel_hi:[1,0]
	s_nop 0
	v_pk_mul_f32 v[62:63], v[38:39], v[62:63]
	s_nop 0
	v_pk_mul_f32 v[60:61], v[60:61], v[62:63]
	s_nop 0
	v_cvt_pk_bf16_f32 v60, v60, v61
	global_store_dword v[6:7], v60, off
	v_lshl_add_u64 v[6:7], v[6:7], 0, s[16:17]
	s_waitcnt vmcnt(7)
	v_and_b32_e32 v56, 0xffff0000, v52
	v_lshlrev_b32_e32 v57, 16, v52
	v_mul_f32_e32 v56, 0x3fb8aa3b, v56
	v_mul_f32_e32 v57, 0x3fb8aa3b, v57
	v_exp_f32_e32 v56, v56
	v_exp_f32_e32 v57, v57
	v_and_b32_e32 v58, 0xffff0000, v53
	v_lshlrev_b32_e32 v59, 16, v53
	v_lshlrev_b32_e32 v60, 16, v54
	v_and_b32_e32 v61, 0xffff0000, v54
	v_pk_fma_f32 v[0:1], v[0:1], v[56:57], v[58:59]
	v_mul_f32_e32 v62, 0x3d372713, v60
	v_mul_f32_e32 v63, 0x3d372713, v61
	v_pk_mul_f32 v[38:39], v[60:61], 0.5 op_sel_hi:[1,0]
	v_mul_f32_e32 v62, v62, v60
	v_mul_f32_e32 v63, v63, v61
	v_fma_f32 v62, v62, v60, v60
	v_fma_f32 v63, v63, v61, v61
	v_mul_f32_e32 v62, 0x3f4c422a, v62
	v_mul_f32_e32 v63, 0x3f4c422a, v63
	v_add_f32_e32 v62, v62, v62
	v_add_f32_e32 v63, v63, v63
	v_mul_f32_e32 v62, 0x3fb8aa3b, v62
	v_mul_f32_e32 v63, 0x3fb8aa3b, v63
	v_exp_f32_e32 v62, v62
	v_exp_f32_e32 v63, v63
	v_lshlrev_b32_e32 v60, 16, v55
	v_and_b32_e32 v61, 0xffff0000, v55
	v_add_f32_e32 v62, 1.0, v62
	v_add_f32_e32 v63, 1.0, v63
	v_rcp_f32_e32 v62, v62
	v_rcp_f32_e32 v63, v63
	v_pk_add_f32 v[60:61], v[0:1], v[60:61] op_sel:[1,0] op_sel_hi:[0,1]
	v_pk_fma_f32 v[62:63], v[62:63], 2.0, 1.0 op_sel_hi:[1,0,0] neg_lo:[1,0,0] neg_hi:[1,0,0]
	s_nop 0
	v_pk_add_f32 v[62:63], v[62:63], 1.0 op_sel_hi:[1,0]
	s_nop 0
	v_pk_mul_f32 v[62:63], v[38:39], v[62:63]
	s_nop 0
	v_pk_mul_f32 v[60:61], v[60:61], v[62:63]
	s_nop 0
	v_cvt_pk_bf16_f32 v60, v60, v61
	global_store_dword v[6:7], v60, off
	v_lshl_add_u64 v[6:7], v[6:7], 0, s[16:17]
	v_lshl_add_u64 v[14:15], v[14:15], 0, s[36:37]
	s_movk_i32 s14, 0xc000
	v_lshl_add_u64 v[4:5], v[4:5], 0, s[14:15]
	s_movk_i32 s0, 0xa000
	s_mov_b32 s1, -1
	v_lshl_add_u64 v[2:3], v[2:3], 0, s[0:1]
	s_add_i32 s12, s12, -8
	s_cmp_eq_u32 s12, 0
	s_cbranch_scc0 .LBB0_181
	s_add_i32 s22, s22, s5
	s_add_i32 s21, s21, s20
	s_cmpk_gt_i32 s22, 0x7f
	s_cbranch_scc0 .LBB0_168

; __device__ void hyena_phase(unsigned char* smem, const Params& p, int l, int order) {
;     ...
;         const float sk = skip[c];
;         __syncthreads();
;         { const u32x4 rw = *(const u32x4*)(rvp + ((size_t)order * 512 + c) * 4096 + tid * 8);
;           const unsigned short e[8] = {(unsigned short)(rw.x & 0xffff), (unsigned short)(rw.x >> 16), (unsigned short)(rw.y & 0xffff), (unsigned short)(rw.y >> 16),
;                                        (unsigned short)(rw.z & 0xffff), (unsigned short)(rw.z >> 16), (unsigned short)(rw.w & 0xffff), (unsigned short)(rw.w >> 16)};
; #pragma unroll
;           for (int m = 0; m < 8; ++m) {
; #pragma unroll
;               for (int k = 0; k < 8; ++k) { const int x = tid * 8 + k - m; if (x >= 0) fs[m * FS + x] = e[k]; } } }
;         for (int idx = tid; idx < 16 * 256; idx += 512) { const int b = idx >> 8, s8 = idx & 255; *(u32x4*)(zs + b * ZS + s8 * 8) = *(const u32x4*)(zin + (size_t)b * SEQ + s8 * 8); }
.LBB0_199:
	s_ashr_i32 s7, s6, 31
	s_lshl_b64 s[0:1], s[6:7], 2
	s_add_u32 s0, s5, s0
	s_addc_u32 s1, s14, s1
	global_load_dword v100, v185, s[0:1]
	s_lshl_b64 s[0:1], s[6:7], 13
	v_lshl_add_u64 v[0:1], v[90:91], 0, s[0:1]
	s_barrier
	global_load_dwordx4 v[0:3], v[0:1], off
	s_lshl_b64 s[12:13], s[6:7], 16
	s_add_u32 s18, s22, s12
	s_addc_u32 s19, s15, s13
	v_ashrrev_i32_e32 v42, 8, v106
	v_lshlrev_b32_e32 v40, 1, v88
	v_ashrrev_i32_e32 v43, 31, v42
	v_and_b32_e32 v46, 0xff0, v40
	v_lshlrev_b64 v[40:41], 12, v[42:43]
	v_mov_b32_e32 v47, 0
	v_lshl_add_u64 v[40:41], s[18:19], 0, v[40:41]
	s_mov_b64 s[20:21], 0x2000
	v_lshl_add_u64 v[40:41], v[40:41], 0, v[46:47]
	v_mul_i32_i24_e32 v44, 0x1010, v42
	global_load_dwordx4 v[8:11], v[40:41], off
	v_lshl_add_u64 v[40:41], v[40:41], 0, s[20:21]
	global_load_dwordx4 v[12:15], v[40:41], off
	v_lshl_add_u64 v[40:41], v[40:41], 0, s[20:21]
	global_load_dwordx4 v[16:19], v[40:41], off
	v_lshl_add_u64 v[40:41], v[40:41], 0, s[20:21]
	global_load_dwordx4 v[20:23], v[40:41], off
	v_lshl_add_u64 v[40:41], v[40:41], 0, s[20:21]
	global_load_dwordx4 v[24:27], v[40:41], off
	v_lshl_add_u64 v[40:41], v[40:41], 0, s[20:21]
	global_load_dwordx4 v[28:31], v[40:41], off
	v_lshl_add_u64 v[40:41], v[40:41], 0, s[20:21]
	global_load_dwordx4 v[32:35], v[40:41], off
	v_lshl_add_u64 v[40:41], v[40:41], 0, s[20:21]
	global_load_dwordx4 v[36:39], v[40:41], off
	v_add_u32_e32 v44, v44, v46
	s_and_saveexec_b64 s[0:1], s[8:9]
	s_cbranch_execz .LBB0_215
	s_waitcnt vmcnt(8)
	ds_write_b128 v107, v[0:3]
	s_or_b64 exec, exec, s[0:1]
	s_and_saveexec_b64 s[0:1], s[10:11]
	s_cbranch_execnz .LBB0_216

; __device__ void hyena_phase(unsigned char* smem, const Params& p, int l, int order) {
;     ...
;           const unsigned short e[8] = {(unsigned short)(rw.x & 0xffff), (unsigned short)(rw.x >> 16), (unsigned short)(rw.y & 0xffff), (unsigned short)(rw.y >> 16),
;                                        (unsigned short)(rw.z & 0xffff), (unsigned short)(rw.z >> 16), (unsigned short)(rw.w & 0xffff), (unsigned short)(rw.w >> 16)};
; #pragma unroll
;           for (int m = 0; m < 8; ++m) {
; #pragma unroll
;               for (int k = 0; k < 8; ++k) { const int x = tid * 8 + k - m; if (x >= 0) fs[m * FS + x] = e[k]; } } }
.LBB0_202:
	s_waitcnt vmcnt(8)
	v_mov_b32_e32 v4, v1
	v_mov_b32_e32 v5, v2
	v_mov_b32_e32 v6, v3
	ds_write_b16_d16_hi v108, v0
	ds_write_b96 v108, v[4:6] offset:2
	s_or_b64 exec, exec, s[0:1]
	s_and_saveexec_b64 s[0:1], s[10:11]
	s_cbranch_execnz .LBB0_218

; __device__ void hyena_phase(unsigned char* smem, const Params& p, int l, int order) {
;     ...
;           const unsigned short e[8] = {(unsigned short)(rw.x & 0xffff), (unsigned short)(rw.x >> 16), (unsigned short)(rw.y & 0xffff), (unsigned short)(rw.y >> 16),
;                                        (unsigned short)(rw.z & 0xffff), (unsigned short)(rw.z >> 16), (unsigned short)(rw.w & 0xffff), (unsigned short)(rw.w >> 16)};
; #pragma unroll
;           for (int m = 0; m < 8; ++m) {
; #pragma unroll
;               for (int k = 0; k < 8; ++k) { const int x = tid * 8 + k - m; if (x >= 0) fs[m * FS + x] = e[k]; } } }
.LBB0_204:
	s_waitcnt vmcnt(8)
	v_mov_b32_e32 v4, v1
	v_mov_b32_e32 v5, v2
	v_mov_b32_e32 v6, v3
	ds_write_b96 v110, v[4:6]
	s_or_b64 exec, exec, s[0:1]
	s_and_saveexec_b64 s[0:1], s[10:11]
	s_cbranch_execnz .LBB0_220

; __device__ void hyena_phase(unsigned char* smem, const Params& p, int l, int order) {
;     ...
;           const unsigned short e[8] = {(unsigned short)(rw.x & 0xffff), (unsigned short)(rw.x >> 16), (unsigned short)(rw.y & 0xffff), (unsigned short)(rw.y >> 16),
;                                        (unsigned short)(rw.z & 0xffff), (unsigned short)(rw.z >> 16), (unsigned short)(rw.w & 0xffff), (unsigned short)(rw.w >> 16)};
; #pragma unroll
;           for (int m = 0; m < 8; ++m) {
; #pragma unroll
;               for (int k = 0; k < 8; ++k) { const int x = tid * 8 + k - m; if (x >= 0) fs[m * FS + x] = e[k]; } } }
.LBB0_206:
	s_waitcnt vmcnt(8)
	ds_write_b16_d16_hi v112, v1
	ds_write_b64 v112, v[2:3] offset:2
	s_or_b64 exec, exec, s[0:1]
	s_and_saveexec_b64 s[0:1], s[10:11]
	s_cbranch_execnz .LBB0_222

; __device__ void hyena_phase(unsigned char* smem, const Params& p, int l, int order) {
;     ...
;           const unsigned short e[8] = {(unsigned short)(rw.x & 0xffff), (unsigned short)(rw.x >> 16), (unsigned short)(rw.y & 0xffff), (unsigned short)(rw.y >> 16),
;                                        (unsigned short)(rw.z & 0xffff), (unsigned short)(rw.z >> 16), (unsigned short)(rw.w & 0xffff), (unsigned short)(rw.w >> 16)};
; #pragma unroll
;           for (int m = 0; m < 8; ++m) {
; #pragma unroll
;               for (int k = 0; k < 8; ++k) { const int x = tid * 8 + k - m; if (x >= 0) fs[m * FS + x] = e[k]; } } }
.LBB0_208:
	s_waitcnt vmcnt(8)
	ds_write_b64 v115, v[2:3]
	s_or_b64 exec, exec, s[0:1]
	s_and_saveexec_b64 s[0:1], s[10:11]
	s_cbranch_execnz .LBB0_224

; __device__ void hyena_phase(unsigned char* smem, const Params& p, int l, int order) {
;     ...
;           const unsigned short e[8] = {(unsigned short)(rw.x & 0xffff), (unsigned short)(rw.x >> 16), (unsigned short)(rw.y & 0xffff), (unsigned short)(rw.y >> 16),
;                                        (unsigned short)(rw.z & 0xffff), (unsigned short)(rw.z >> 16), (unsigned short)(rw.w & 0xffff), (unsigned short)(rw.w >> 16)};
; #pragma unroll
;           for (int m = 0; m < 8; ++m) {
; #pragma unroll
;               for (int k = 0; k < 8; ++k) { const int x = tid * 8 + k - m; if (x >= 0) fs[m * FS + x] = e[k]; } } }
.LBB0_210:
	s_waitcnt vmcnt(8)
	ds_write_b16_d16_hi v117, v2
	ds_write_b32 v117, v3 offset:2
	s_or_b64 exec, exec, s[0:1]
	s_and_saveexec_b64 s[0:1], s[10:11]
	s_cbranch_execnz .LBB0_226

; __device__ void hyena_phase(unsigned char* smem, const Params& p, int l, int order) {
;     ...
;           const unsigned short e[8] = {(unsigned short)(rw.x & 0xffff), (unsigned short)(rw.x >> 16), (unsigned short)(rw.y & 0xffff), (unsigned short)(rw.y >> 16),
;                                        (unsigned short)(rw.z & 0xffff), (unsigned short)(rw.z >> 16), (unsigned short)(rw.w & 0xffff), (unsigned short)(rw.w >> 16)};
; #pragma unroll
;           for (int m = 0; m < 8; ++m) {
; #pragma unroll
;               for (int k = 0; k < 8; ++k) { const int x = tid * 8 + k - m; if (x >= 0) fs[m * FS + x] = e[k]; } } }
.LBB0_212:
	s_waitcnt vmcnt(8)
	ds_write_b32 v120, v3
	s_or_b64 exec, exec, s[0:1]
	s_and_saveexec_b64 s[0:1], s[10:11]
	s_cbranch_execnz .LBB0_228

; __device__ void hyena_phase(unsigned char* smem, const Params& p, int l, int order) {
;     ...
;           const unsigned short e[8] = {(unsigned short)(rw.x & 0xffff), (unsigned short)(rw.x >> 16), (unsigned short)(rw.y & 0xffff), (unsigned short)(rw.y >> 16),
;                                        (unsigned short)(rw.z & 0xffff), (unsigned short)(rw.z >> 16), (unsigned short)(rw.w & 0xffff), (unsigned short)(rw.w >> 16)};
; #pragma unroll
;           for (int m = 0; m < 8; ++m) {
; #pragma unroll
;               for (int k = 0; k < 8; ++k) { const int x = tid * 8 + k - m; if (x >= 0) fs[m * FS + x] = e[k]; } } }
;         for (int idx = tid; idx < 16 * 256; idx += 512) { const int b = idx >> 8, s8 = idx & 255; *(u32x4*)(zs + b * ZS + s8 * 8) = *(const u32x4*)(zin + (size_t)b * SEQ + s8 * 8); }
.LBB0_214:
	s_waitcnt vmcnt(8)
	ds_write_b16_d16_hi v123, v3
	s_or_b64 exec, exec, s[0:1]
	s_lshl_b64 s[12:13], s[6:7], 16
	s_and_saveexec_b64 s[16:17], vcc
	s_cbranch_execz .LBB0_232
	s_branch .LBB0_230

; __device__ void hyena_phase(unsigned char* smem, const Params& p, int l, int order) {
;     ...
;           const unsigned short e[8] = {(unsigned short)(rw.x & 0xffff), (unsigned short)(rw.x >> 16), (unsigned short)(rw.y & 0xffff), (unsigned short)(rw.y >> 16),
;                                        (unsigned short)(rw.z & 0xffff), (unsigned short)(rw.z >> 16), (unsigned short)(rw.w & 0xffff), (unsigned short)(rw.w >> 16)};
; #pragma unroll
;           for (int m = 0; m < 8; ++m) {
; #pragma unroll
;               for (int k = 0; k < 8; ++k) { const int x = tid * 8 + k - m; if (x >= 0) fs[m * FS + x] = e[k]; } } }
.LBB0_216:
	s_waitcnt vmcnt(8)
	ds_write_b16 v109, v0
	s_or_b64 exec, exec, s[0:1]
	s_and_saveexec_b64 s[0:1], s[8:9]
	s_cbranch_execnz .LBB0_202

; __device__ void hyena_phase(unsigned char* smem, const Params& p, int l, int order) {
;     ...
;           const unsigned short e[8] = {(unsigned short)(rw.x & 0xffff), (unsigned short)(rw.x >> 16), (unsigned short)(rw.y & 0xffff), (unsigned short)(rw.y >> 16),
;                                        (unsigned short)(rw.z & 0xffff), (unsigned short)(rw.z >> 16), (unsigned short)(rw.w & 0xffff), (unsigned short)(rw.w >> 16)};
; #pragma unroll
;           for (int m = 0; m < 8; ++m) {
; #pragma unroll
;               for (int k = 0; k < 8; ++k) { const int x = tid * 8 + k - m; if (x >= 0) fs[m * FS + x] = e[k]; } } }
.LBB0_218:
	s_waitcnt vmcnt(8)
	ds_write_b32 v111, v0
	s_or_b64 exec, exec, s[0:1]
	s_and_saveexec_b64 s[0:1], s[8:9]
	s_cbranch_execnz .LBB0_204

; __device__ void hyena_phase(unsigned char* smem, const Params& p, int l, int order) {
;     ...
;           const unsigned short e[8] = {(unsigned short)(rw.x & 0xffff), (unsigned short)(rw.x >> 16), (unsigned short)(rw.y & 0xffff), (unsigned short)(rw.y >> 16),
;                                        (unsigned short)(rw.z & 0xffff), (unsigned short)(rw.z >> 16), (unsigned short)(rw.w & 0xffff), (unsigned short)(rw.w >> 16)};
; #pragma unroll
;           for (int m = 0; m < 8; ++m) {
; #pragma unroll
;               for (int k = 0; k < 8; ++k) { const int x = tid * 8 + k - m; if (x >= 0) fs[m * FS + x] = e[k]; } } }
.LBB0_220:
	s_waitcnt vmcnt(8)
	ds_write_b32 v113, v0
	ds_write_b16 v114, v1
	s_or_b64 exec, exec, s[0:1]
	s_and_saveexec_b64 s[0:1], s[8:9]
	s_cbranch_execnz .LBB0_206

; __device__ void hyena_phase(unsigned char* smem, const Params& p, int l, int order) {
;     ...
;           const unsigned short e[8] = {(unsigned short)(rw.x & 0xffff), (unsigned short)(rw.x >> 16), (unsigned short)(rw.y & 0xffff), (unsigned short)(rw.y >> 16),
;                                        (unsigned short)(rw.z & 0xffff), (unsigned short)(rw.z >> 16), (unsigned short)(rw.w & 0xffff), (unsigned short)(rw.w >> 16)};
; #pragma unroll
;           for (int m = 0; m < 8; ++m) {
; #pragma unroll
;               for (int k = 0; k < 8; ++k) { const int x = tid * 8 + k - m; if (x >= 0) fs[m * FS + x] = e[k]; } } }
.LBB0_222:
	s_waitcnt vmcnt(8)
	ds_write_b64 v116, v[0:1]
	s_or_b64 exec, exec, s[0:1]
	s_and_saveexec_b64 s[0:1], s[8:9]
	s_cbranch_execnz .LBB0_208

; __device__ void hyena_phase(unsigned char* smem, const Params& p, int l, int order) {
;     ...
;           const unsigned short e[8] = {(unsigned short)(rw.x & 0xffff), (unsigned short)(rw.x >> 16), (unsigned short)(rw.y & 0xffff), (unsigned short)(rw.y >> 16),
;                                        (unsigned short)(rw.z & 0xffff), (unsigned short)(rw.z >> 16), (unsigned short)(rw.w & 0xffff), (unsigned short)(rw.w >> 16)};
; #pragma unroll
;           for (int m = 0; m < 8; ++m) {
; #pragma unroll
;               for (int k = 0; k < 8; ++k) { const int x = tid * 8 + k - m; if (x >= 0) fs[m * FS + x] = e[k]; } } }
.LBB0_224:
	s_waitcnt vmcnt(8)
	ds_write_b64 v118, v[0:1]
	ds_write_b16 v119, v2
	s_or_b64 exec, exec, s[0:1]
	s_and_saveexec_b64 s[0:1], s[8:9]
	s_cbranch_execnz .LBB0_210

; __device__ void hyena_phase(unsigned char* smem, const Params& p, int l, int order) {
;     ...
;           const unsigned short e[8] = {(unsigned short)(rw.x & 0xffff), (unsigned short)(rw.x >> 16), (unsigned short)(rw.y & 0xffff), (unsigned short)(rw.y >> 16),
;                                        (unsigned short)(rw.z & 0xffff), (unsigned short)(rw.z >> 16), (unsigned short)(rw.w & 0xffff), (unsigned short)(rw.w >> 16)};
; #pragma unroll
;           for (int m = 0; m < 8; ++m) {
; #pragma unroll
;               for (int k = 0; k < 8; ++k) { const int x = tid * 8 + k - m; if (x >= 0) fs[m * FS + x] = e[k]; } } }
.LBB0_226:
	s_waitcnt vmcnt(8)
	ds_write2_b32 v121, v0, v1 offset1:1
	ds_write_b32 v122, v2
	s_or_b64 exec, exec, s[0:1]
	s_and_saveexec_b64 s[0:1], s[8:9]
	s_cbranch_execnz .LBB0_212

; __device__ void hyena_phase(unsigned char* smem, const Params& p, int l, int order) {
;     ...
;           const unsigned short e[8] = {(unsigned short)(rw.x & 0xffff), (unsigned short)(rw.x >> 16), (unsigned short)(rw.y & 0xffff), (unsigned short)(rw.y >> 16),
;                                        (unsigned short)(rw.z & 0xffff), (unsigned short)(rw.z >> 16), (unsigned short)(rw.w & 0xffff), (unsigned short)(rw.w >> 16)};
; #pragma unroll
;           for (int m = 0; m < 8; ++m) {
; #pragma unroll
;               for (int k = 0; k < 8; ++k) { const int x = tid * 8 + k - m; if (x >= 0) fs[m * FS + x] = e[k]; } } }
.LBB0_228:
	s_waitcnt vmcnt(8)
	ds_write_b96 v124, v[0:2]
	ds_write_b16 v125, v3
	s_or_b64 exec, exec, s[0:1]
	s_and_saveexec_b64 s[0:1], s[8:9]
	s_cbranch_execnz .LBB0_214

; __device__ void hyena_phase(unsigned char* smem, const Params& p, int l, int order) {
;     ...
;         for (int idx = tid; idx < 16 * 256; idx += 512) { const int b = idx >> 8, s8 = idx & 255; *(u32x4*)(zs + b * ZS + s8 * 8) = *(const u32x4*)(zin + (size_t)b * SEQ + s8 * 8); }
.LBB0_230:
	s_waitcnt vmcnt(7)
	ds_write_b128 v44, v[8:11]
	s_waitcnt vmcnt(6)
	ds_write_b128 v44, v[12:15] offset:8224
	s_waitcnt vmcnt(5)
	ds_write_b128 v44, v[16:19] offset:16448
	s_waitcnt vmcnt(4)
	ds_write_b128 v44, v[20:23] offset:24672
	s_waitcnt vmcnt(3)
	ds_write_b128 v44, v[24:27] offset:32896
	s_waitcnt vmcnt(2)
	ds_write_b128 v44, v[28:31] offset:41120
	s_waitcnt vmcnt(1)
	ds_write_b128 v44, v[32:35] offset:49344
	s_waitcnt vmcnt(0)
	ds_write_b128 v44, v[36:39] offset:57568
